# phase 0: waves 4-7 do the row pass first and the weight transposes after (waves 0-3 the reverse) so the bandwidth-bound and latency-bound halves overlap
# speedup vs baseline: 1.0223x; 1.0043x over previous
.LBB0_518:
	s_mov_b32 s99, 0
	v_readfirstlane_b32 s98, v197
	s_lshr_b32 s98, s98, 8
	s_cmp_eq_u32 s98, 0
	s_cbranch_scc1 .Lp0_tr
	v_readlane_b32 s0, v254, 59
	v_readlane_b32 s1, v254, 60
	s_nop 3
	s_load_dword s2, s[0:1], 0x0
	s_waitcnt lgkmcnt(0)
	s_cmpk_lg_u32 s2, 0x100
	s_cbranch_scc1 .Lp0_tr
	s_mov_b32 s99, 1
	s_branch .Lrow0_fast

.LBB0_656:
	s_or_b64 exec, exec, s[30:31]
	s_cmp_eq_u32 s99, 2
	s_cbranch_scc1 .Lrow0_done
	v_readlane_b32 s0, v254, 59
	v_readlane_b32 s1, v254, 60
	s_nop 3
	s_load_dword s2, s[0:1], 0x0
	s_waitcnt lgkmcnt(0)
	s_cmpk_lg_u32 s2, 0x100
	s_cbranch_scc1 .Lrow0_generic
.Lrow0_fast:
	v_readlane_b32 s0, v254, 58
	v_readfirstlane_b32 s1, v197
	v_readlane_b32 s4, v254, 42
	v_readlane_b32 s5, v254, 43
	v_readlane_b32 s6, v254, 44
	v_readlane_b32 s7, v254, 45
	v_readlane_b32 s8, v254, 46
	v_readlane_b32 s9, v254, 47
	v_and_b32_e32 v164, 63, v197
	v_lshlrev_b32_e32 v165, 3, v164
	v_lshlrev_b32_e32 v164, 4, v164
	s_lshr_b32 s1, s1, 6
	s_lshl_b32 s0, s0, 3
	s_add_i32 s20, s0, s1
	s_lshl_b32 s0, s20, 12
	s_add_u32 s10, s4, s0
	s_addc_u32 s11, s5, 0
	s_lshl_b32 s0, s20, 11
	s_add_u32 s12, s90, s0
	s_addc_u32 s13, s91, 0
	global_load_dwordx4 v[132:135], v164, s[8:9] offset:0
	global_load_dwordx4 v[136:139], v164, s[8:9] offset:1024
	global_load_dwordx4 v[140:143], v164, s[8:9] offset:2048
	global_load_dwordx4 v[144:147], v164, s[8:9] offset:3072
	s_mov_b64 s[22:23], s[10:11]
	global_load_dwordx4 v[4:7], v164, s[22:23] offset:0 nt
	global_load_dwordx4 v[8:11], v164, s[22:23] offset:1024 nt
	global_load_dwordx4 v[12:15], v164, s[22:23] offset:2048 nt
	global_load_dwordx4 v[16:19], v164, s[22:23] offset:3072 nt
	s_add_u32 s22, s10, 0x800000
	s_addc_u32 s23, s11, 0
	global_load_dwordx4 v[20:23], v164, s[22:23] offset:0 nt
	global_load_dwordx4 v[24:27], v164, s[22:23] offset:1024 nt
	global_load_dwordx4 v[28:31], v164, s[22:23] offset:2048 nt
	global_load_dwordx4 v[32:35], v164, s[22:23] offset:3072 nt
	s_add_u32 s22, s10, 0x1000000
	s_addc_u32 s23, s11, 0
	global_load_dwordx4 v[36:39], v164, s[22:23] offset:0 nt
	global_load_dwordx4 v[40:43], v164, s[22:23] offset:1024 nt
	global_load_dwordx4 v[44:47], v164, s[22:23] offset:2048 nt
	global_load_dwordx4 v[48:51], v164, s[22:23] offset:3072 nt
	s_add_u32 s22, s10, 0x1800000
	s_addc_u32 s23, s11, 0
	global_load_dwordx4 v[52:55], v164, s[22:23] offset:0 nt
	global_load_dwordx4 v[56:59], v164, s[22:23] offset:1024 nt
	global_load_dwordx4 v[60:63], v164, s[22:23] offset:2048 nt
	global_load_dwordx4 v[64:67], v164, s[22:23] offset:3072 nt
	s_add_u32 s22, s10, 0x2000000
	s_addc_u32 s23, s11, 0
	global_load_dwordx4 v[68:71], v164, s[22:23] offset:0 nt
	global_load_dwordx4 v[72:75], v164, s[22:23] offset:1024 nt
	global_load_dwordx4 v[76:79], v164, s[22:23] offset:2048 nt
	global_load_dwordx4 v[80:83], v164, s[22:23] offset:3072 nt
	s_add_u32 s22, s10, 0x2800000
	s_addc_u32 s23, s11, 0
	global_load_dwordx4 v[84:87], v164, s[22:23] offset:0 nt
	global_load_dwordx4 v[88:91], v164, s[22:23] offset:1024 nt
	global_load_dwordx4 v[92:95], v164, s[22:23] offset:2048 nt
	global_load_dwordx4 v[96:99], v164, s[22:23] offset:3072 nt
	s_add_u32 s22, s10, 0x3000000
	s_addc_u32 s23, s11, 0
	global_load_dwordx4 v[100:103], v164, s[22:23] offset:0 nt
	global_load_dwordx4 v[104:107], v164, s[22:23] offset:1024 nt
	global_load_dwordx4 v[108:111], v164, s[22:23] offset:2048 nt
	global_load_dwordx4 v[112:115], v164, s[22:23] offset:3072 nt
	s_add_u32 s22, s10, 0x3800000
	s_addc_u32 s23, s11, 0
	global_load_dwordx4 v[116:119], v164, s[22:23] offset:0 nt
	global_load_dwordx4 v[120:123], v164, s[22:23] offset:1024 nt
	global_load_dwordx4 v[124:127], v164, s[22:23] offset:2048 nt
	global_load_dwordx4 v[128:131], v164, s[22:23] offset:3072 nt
	s_waitcnt vmcnt(28)
	v_pk_mul_f32 v[148:149], v[4:5], v[4:5]
	v_pk_fma_f32 v[148:149], v[6:7], v[6:7], v[148:149]
	v_pk_fma_f32 v[148:149], v[8:9], v[8:9], v[148:149]
	v_pk_fma_f32 v[148:149], v[10:11], v[10:11], v[148:149]
	v_pk_fma_f32 v[148:149], v[12:13], v[12:13], v[148:149]
	v_pk_fma_f32 v[148:149], v[14:15], v[14:15], v[148:149]
	v_pk_fma_f32 v[148:149], v[16:17], v[16:17], v[148:149]
	v_pk_fma_f32 v[148:149], v[18:19], v[18:19], v[148:149]
	s_waitcnt vmcnt(24)
	v_pk_mul_f32 v[150:151], v[20:21], v[20:21]
	v_pk_fma_f32 v[150:151], v[22:23], v[22:23], v[150:151]
	v_pk_fma_f32 v[150:151], v[24:25], v[24:25], v[150:151]
	v_pk_fma_f32 v[150:151], v[26:27], v[26:27], v[150:151]
	v_pk_fma_f32 v[150:151], v[28:29], v[28:29], v[150:151]
	v_pk_fma_f32 v[150:151], v[30:31], v[30:31], v[150:151]
	v_pk_fma_f32 v[150:151], v[32:33], v[32:33], v[150:151]
	v_pk_fma_f32 v[150:151], v[34:35], v[34:35], v[150:151]
	s_waitcnt vmcnt(20)
	v_pk_mul_f32 v[152:153], v[36:37], v[36:37]
	v_pk_fma_f32 v[152:153], v[38:39], v[38:39], v[152:153]
	v_pk_fma_f32 v[152:153], v[40:41], v[40:41], v[152:153]
	v_pk_fma_f32 v[152:153], v[42:43], v[42:43], v[152:153]
	v_pk_fma_f32 v[152:153], v[44:45], v[44:45], v[152:153]
	v_pk_fma_f32 v[152:153], v[46:47], v[46:47], v[152:153]
	v_pk_fma_f32 v[152:153], v[48:49], v[48:49], v[152:153]
	v_pk_fma_f32 v[152:153], v[50:51], v[50:51], v[152:153]
	s_waitcnt vmcnt(16)
	v_pk_mul_f32 v[154:155], v[52:53], v[52:53]
	v_pk_fma_f32 v[154:155], v[54:55], v[54:55], v[154:155]
	v_pk_fma_f32 v[154:155], v[56:57], v[56:57], v[154:155]
	v_pk_fma_f32 v[154:155], v[58:59], v[58:59], v[154:155]
	v_pk_fma_f32 v[154:155], v[60:61], v[60:61], v[154:155]
	v_pk_fma_f32 v[154:155], v[62:63], v[62:63], v[154:155]
	v_pk_fma_f32 v[154:155], v[64:65], v[64:65], v[154:155]
	v_pk_fma_f32 v[154:155], v[66:67], v[66:67], v[154:155]
	v_add_f32_e32 v148, v148, v149
	v_add_f32_e32 v150, v150, v151
	v_add_f32_e32 v152, v152, v153
	v_add_f32_e32 v154, v154, v155
	s_nop 0
	v_add_f32_dpp v148, v148, v148 quad_perm:[1,0,3,2] row_mask:0xf bank_mask:0xf
	v_add_f32_dpp v150, v150, v150 quad_perm:[1,0,3,2] row_mask:0xf bank_mask:0xf
	v_add_f32_dpp v152, v152, v152 quad_perm:[1,0,3,2] row_mask:0xf bank_mask:0xf
	v_add_f32_dpp v154, v154, v154 quad_perm:[1,0,3,2] row_mask:0xf bank_mask:0xf
	s_nop 0
	v_add_f32_dpp v148, v148, v148 quad_perm:[2,3,0,1] row_mask:0xf bank_mask:0xf
	v_add_f32_dpp v150, v150, v150 quad_perm:[2,3,0,1] row_mask:0xf bank_mask:0xf
	v_add_f32_dpp v152, v152, v152 quad_perm:[2,3,0,1] row_mask:0xf bank_mask:0xf
	v_add_f32_dpp v154, v154, v154 quad_perm:[2,3,0,1] row_mask:0xf bank_mask:0xf
	s_nop 0
	v_add_f32_dpp v148, v148, v148 row_half_mirror row_mask:0xf bank_mask:0xf
	v_add_f32_dpp v150, v150, v150 row_half_mirror row_mask:0xf bank_mask:0xf
	v_add_f32_dpp v152, v152, v152 row_half_mirror row_mask:0xf bank_mask:0xf
	v_add_f32_dpp v154, v154, v154 row_half_mirror row_mask:0xf bank_mask:0xf
	s_nop 0
	v_add_f32_dpp v148, v148, v148 row_mirror row_mask:0xf bank_mask:0xf
	v_add_f32_dpp v150, v150, v150 row_mirror row_mask:0xf bank_mask:0xf
	v_add_f32_dpp v152, v152, v152 row_mirror row_mask:0xf bank_mask:0xf
	v_add_f32_dpp v154, v154, v154 row_mirror row_mask:0xf bank_mask:0xf
	s_nop 0
	v_add_f32_dpp v148, v148, v148 row_bcast:15 row_mask:0xa bank_mask:0xf
	v_add_f32_dpp v150, v150, v150 row_bcast:15 row_mask:0xa bank_mask:0xf
	v_add_f32_dpp v152, v152, v152 row_bcast:15 row_mask:0xa bank_mask:0xf
	v_add_f32_dpp v154, v154, v154 row_bcast:15 row_mask:0xa bank_mask:0xf
	s_nop 0
	v_add_f32_dpp v148, v148, v148 row_bcast:31 row_mask:0xc bank_mask:0xf
	v_add_f32_dpp v150, v150, v150 row_bcast:31 row_mask:0xc bank_mask:0xf
	v_add_f32_dpp v152, v152, v152 row_bcast:31 row_mask:0xc bank_mask:0xf
	v_add_f32_dpp v154, v154, v154 row_bcast:31 row_mask:0xc bank_mask:0xf
	s_nop 1
	v_readlane_b32 s0, v148, 63
	v_readlane_b32 s1, v150, 63
	v_readlane_b32 s2, v152, 63
	v_readlane_b32 s3, v154, 63
	s_nop 1
	v_mov_b32_e32 v156, s0
	v_mov_b32_e32 v158, s1
	v_mov_b32_e32 v160, s2
	v_mov_b32_e32 v162, s3
	v_fmamk_f32 v156, v156, 0x3a800000, v196
	v_fmamk_f32 v158, v158, 0x3a800000, v196
	v_fmamk_f32 v160, v160, 0x3a800000, v196
	v_fmamk_f32 v162, v162, 0x3a800000, v196
	v_rsq_f32_e32 v156, v156
	v_rsq_f32_e32 v158, v158
	v_rsq_f32_e32 v160, v160
	v_rsq_f32_e32 v162, v162
	s_nop 0
	v_pk_mul_f32 v[4:5], v[4:5], v[156:157] op_sel_hi:[1,0]
	v_pk_mul_f32 v[6:7], v[6:7], v[156:157] op_sel_hi:[1,0]
	v_pk_mul_f32 v[8:9], v[8:9], v[156:157] op_sel_hi:[1,0]
	v_pk_mul_f32 v[10:11], v[10:11], v[156:157] op_sel_hi:[1,0]
	v_pk_mul_f32 v[12:13], v[12:13], v[156:157] op_sel_hi:[1,0]
	v_pk_mul_f32 v[14:15], v[14:15], v[156:157] op_sel_hi:[1,0]
	v_pk_mul_f32 v[16:17], v[16:17], v[156:157] op_sel_hi:[1,0]
	v_pk_mul_f32 v[18:19], v[18:19], v[156:157] op_sel_hi:[1,0]
	v_pk_mul_f32 v[4:5], v[4:5], v[132:133]
	v_pk_mul_f32 v[6:7], v[6:7], v[134:135]
	v_pk_mul_f32 v[8:9], v[8:9], v[136:137]
	v_pk_mul_f32 v[10:11], v[10:11], v[138:139]
	v_pk_mul_f32 v[12:13], v[12:13], v[140:141]
	v_pk_mul_f32 v[14:15], v[14:15], v[142:143]
	v_pk_mul_f32 v[16:17], v[16:17], v[144:145]
	v_pk_mul_f32 v[18:19], v[18:19], v[146:147]
	v_cvt_pk_bf16_f32 v4, v4, v5
	v_cvt_pk_bf16_f32 v5, v6, v7
	v_cvt_pk_bf16_f32 v6, v8, v9
	v_cvt_pk_bf16_f32 v7, v10, v11
	v_cvt_pk_bf16_f32 v8, v12, v13
	v_cvt_pk_bf16_f32 v9, v14, v15
	v_cvt_pk_bf16_f32 v10, v16, v17
	v_cvt_pk_bf16_f32 v11, v18, v19
	s_mov_b64 s[24:25], s[12:13]
	global_store_dwordx2 v165, v[4:5], s[24:25] offset:0
	global_store_dwordx2 v165, v[6:7], s[24:25] offset:512
	global_store_dwordx2 v165, v[8:9], s[24:25] offset:1024
	global_store_dwordx2 v165, v[10:11], s[24:25] offset:1536
	v_pk_mul_f32 v[20:21], v[20:21], v[158:159] op_sel_hi:[1,0]
	v_pk_mul_f32 v[22:23], v[22:23], v[158:159] op_sel_hi:[1,0]
	v_pk_mul_f32 v[24:25], v[24:25], v[158:159] op_sel_hi:[1,0]
	v_pk_mul_f32 v[26:27], v[26:27], v[158:159] op_sel_hi:[1,0]
	v_pk_mul_f32 v[28:29], v[28:29], v[158:159] op_sel_hi:[1,0]
	v_pk_mul_f32 v[30:31], v[30:31], v[158:159] op_sel_hi:[1,0]
	v_pk_mul_f32 v[32:33], v[32:33], v[158:159] op_sel_hi:[1,0]
	v_pk_mul_f32 v[34:35], v[34:35], v[158:159] op_sel_hi:[1,0]
	v_pk_mul_f32 v[20:21], v[20:21], v[132:133]
	v_pk_mul_f32 v[22:23], v[22:23], v[134:135]
	v_pk_mul_f32 v[24:25], v[24:25], v[136:137]
	v_pk_mul_f32 v[26:27], v[26:27], v[138:139]
	v_pk_mul_f32 v[28:29], v[28:29], v[140:141]
	v_pk_mul_f32 v[30:31], v[30:31], v[142:143]
	v_pk_mul_f32 v[32:33], v[32:33], v[144:145]
	v_pk_mul_f32 v[34:35], v[34:35], v[146:147]
	v_cvt_pk_bf16_f32 v20, v20, v21
	v_cvt_pk_bf16_f32 v21, v22, v23
	v_cvt_pk_bf16_f32 v22, v24, v25
	v_cvt_pk_bf16_f32 v23, v26, v27
	v_cvt_pk_bf16_f32 v24, v28, v29
	v_cvt_pk_bf16_f32 v25, v30, v31
	v_cvt_pk_bf16_f32 v26, v32, v33
	v_cvt_pk_bf16_f32 v27, v34, v35
	s_add_u32 s24, s12, 0x400000
	s_addc_u32 s25, s13, 0
	global_store_dwordx2 v165, v[20:21], s[24:25] offset:0
	global_store_dwordx2 v165, v[22:23], s[24:25] offset:512
	global_store_dwordx2 v165, v[24:25], s[24:25] offset:1024
	global_store_dwordx2 v165, v[26:27], s[24:25] offset:1536
	v_pk_mul_f32 v[36:37], v[36:37], v[160:161] op_sel_hi:[1,0]
	v_pk_mul_f32 v[38:39], v[38:39], v[160:161] op_sel_hi:[1,0]
	v_pk_mul_f32 v[40:41], v[40:41], v[160:161] op_sel_hi:[1,0]
	v_pk_mul_f32 v[42:43], v[42:43], v[160:161] op_sel_hi:[1,0]
	v_pk_mul_f32 v[44:45], v[44:45], v[160:161] op_sel_hi:[1,0]
	v_pk_mul_f32 v[46:47], v[46:47], v[160:161] op_sel_hi:[1,0]
	v_pk_mul_f32 v[48:49], v[48:49], v[160:161] op_sel_hi:[1,0]
	v_pk_mul_f32 v[50:51], v[50:51], v[160:161] op_sel_hi:[1,0]
	v_pk_mul_f32 v[36:37], v[36:37], v[132:133]
	v_pk_mul_f32 v[38:39], v[38:39], v[134:135]
	v_pk_mul_f32 v[40:41], v[40:41], v[136:137]
	v_pk_mul_f32 v[42:43], v[42:43], v[138:139]
	v_pk_mul_f32 v[44:45], v[44:45], v[140:141]
	v_pk_mul_f32 v[46:47], v[46:47], v[142:143]
	v_pk_mul_f32 v[48:49], v[48:49], v[144:145]
	v_pk_mul_f32 v[50:51], v[50:51], v[146:147]
	v_cvt_pk_bf16_f32 v36, v36, v37
	v_cvt_pk_bf16_f32 v37, v38, v39
	v_cvt_pk_bf16_f32 v38, v40, v41
	v_cvt_pk_bf16_f32 v39, v42, v43
	v_cvt_pk_bf16_f32 v40, v44, v45
	v_cvt_pk_bf16_f32 v41, v46, v47
	v_cvt_pk_bf16_f32 v42, v48, v49
	v_cvt_pk_bf16_f32 v43, v50, v51
	s_add_u32 s24, s12, 0x800000
	s_addc_u32 s25, s13, 0
	global_store_dwordx2 v165, v[36:37], s[24:25] offset:0
	global_store_dwordx2 v165, v[38:39], s[24:25] offset:512
	global_store_dwordx2 v165, v[40:41], s[24:25] offset:1024
	global_store_dwordx2 v165, v[42:43], s[24:25] offset:1536
	v_pk_mul_f32 v[52:53], v[52:53], v[162:163] op_sel_hi:[1,0]
	v_pk_mul_f32 v[54:55], v[54:55], v[162:163] op_sel_hi:[1,0]
	v_pk_mul_f32 v[56:57], v[56:57], v[162:163] op_sel_hi:[1,0]
	v_pk_mul_f32 v[58:59], v[58:59], v[162:163] op_sel_hi:[1,0]
	v_pk_mul_f32 v[60:61], v[60:61], v[162:163] op_sel_hi:[1,0]
	v_pk_mul_f32 v[62:63], v[62:63], v[162:163] op_sel_hi:[1,0]
	v_pk_mul_f32 v[64:65], v[64:65], v[162:163] op_sel_hi:[1,0]
	v_pk_mul_f32 v[66:67], v[66:67], v[162:163] op_sel_hi:[1,0]
	v_pk_mul_f32 v[52:53], v[52:53], v[132:133]
	v_pk_mul_f32 v[54:55], v[54:55], v[134:135]
	v_pk_mul_f32 v[56:57], v[56:57], v[136:137]
	v_pk_mul_f32 v[58:59], v[58:59], v[138:139]
	v_pk_mul_f32 v[60:61], v[60:61], v[140:141]
	v_pk_mul_f32 v[62:63], v[62:63], v[142:143]
	v_pk_mul_f32 v[64:65], v[64:65], v[144:145]
	v_pk_mul_f32 v[66:67], v[66:67], v[146:147]
	v_cvt_pk_bf16_f32 v52, v52, v53
	v_cvt_pk_bf16_f32 v53, v54, v55
	v_cvt_pk_bf16_f32 v54, v56, v57
	v_cvt_pk_bf16_f32 v55, v58, v59
	v_cvt_pk_bf16_f32 v56, v60, v61
	v_cvt_pk_bf16_f32 v57, v62, v63
	v_cvt_pk_bf16_f32 v58, v64, v65
	v_cvt_pk_bf16_f32 v59, v66, v67
	s_add_u32 s24, s12, 0xc00000
	s_addc_u32 s25, s13, 0
	global_store_dwordx2 v165, v[52:53], s[24:25] offset:0
	global_store_dwordx2 v165, v[54:55], s[24:25] offset:512
	global_store_dwordx2 v165, v[56:57], s[24:25] offset:1024
	global_store_dwordx2 v165, v[58:59], s[24:25] offset:1536
	s_add_u32 s22, s10, 0x4000000
	s_addc_u32 s23, s11, 0
	global_load_dwordx4 v[4:7], v164, s[22:23] offset:0 nt
	global_load_dwordx4 v[8:11], v164, s[22:23] offset:1024 nt
	global_load_dwordx4 v[12:15], v164, s[22:23] offset:2048 nt
	global_load_dwordx4 v[16:19], v164, s[22:23] offset:3072 nt
	s_add_u32 s22, s10, 0x4800000
	s_addc_u32 s23, s11, 0
	global_load_dwordx4 v[20:23], v164, s[22:23] offset:0 nt
	global_load_dwordx4 v[24:27], v164, s[22:23] offset:1024 nt
	global_load_dwordx4 v[28:31], v164, s[22:23] offset:2048 nt
	global_load_dwordx4 v[32:35], v164, s[22:23] offset:3072 nt
	s_add_u32 s22, s10, 0x5000000
	s_addc_u32 s23, s11, 0
	global_load_dwordx4 v[36:39], v164, s[22:23] offset:0 nt
	global_load_dwordx4 v[40:43], v164, s[22:23] offset:1024 nt
	global_load_dwordx4 v[44:47], v164, s[22:23] offset:2048 nt
	global_load_dwordx4 v[48:51], v164, s[22:23] offset:3072 nt
	s_add_u32 s22, s10, 0x5800000
	s_addc_u32 s23, s11, 0
	global_load_dwordx4 v[52:55], v164, s[22:23] offset:0 nt
	global_load_dwordx4 v[56:59], v164, s[22:23] offset:1024 nt
	global_load_dwordx4 v[60:63], v164, s[22:23] offset:2048 nt
	global_load_dwordx4 v[64:67], v164, s[22:23] offset:3072 nt
	s_waitcnt vmcnt(44)
	v_pk_mul_f32 v[148:149], v[68:69], v[68:69]
	v_pk_fma_f32 v[148:149], v[70:71], v[70:71], v[148:149]
	v_pk_fma_f32 v[148:149], v[72:73], v[72:73], v[148:149]
	v_pk_fma_f32 v[148:149], v[74:75], v[74:75], v[148:149]
	v_pk_fma_f32 v[148:149], v[76:77], v[76:77], v[148:149]
	v_pk_fma_f32 v[148:149], v[78:79], v[78:79], v[148:149]
	v_pk_fma_f32 v[148:149], v[80:81], v[80:81], v[148:149]
	v_pk_fma_f32 v[148:149], v[82:83], v[82:83], v[148:149]
	s_waitcnt vmcnt(40)
	v_pk_mul_f32 v[150:151], v[84:85], v[84:85]
	v_pk_fma_f32 v[150:151], v[86:87], v[86:87], v[150:151]
	v_pk_fma_f32 v[150:151], v[88:89], v[88:89], v[150:151]
	v_pk_fma_f32 v[150:151], v[90:91], v[90:91], v[150:151]
	v_pk_fma_f32 v[150:151], v[92:93], v[92:93], v[150:151]
	v_pk_fma_f32 v[150:151], v[94:95], v[94:95], v[150:151]
	v_pk_fma_f32 v[150:151], v[96:97], v[96:97], v[150:151]
	v_pk_fma_f32 v[150:151], v[98:99], v[98:99], v[150:151]
	s_waitcnt vmcnt(36)
	v_pk_mul_f32 v[152:153], v[100:101], v[100:101]
	v_pk_fma_f32 v[152:153], v[102:103], v[102:103], v[152:153]
	v_pk_fma_f32 v[152:153], v[104:105], v[104:105], v[152:153]
	v_pk_fma_f32 v[152:153], v[106:107], v[106:107], v[152:153]
	v_pk_fma_f32 v[152:153], v[108:109], v[108:109], v[152:153]
	v_pk_fma_f32 v[152:153], v[110:111], v[110:111], v[152:153]
	v_pk_fma_f32 v[152:153], v[112:113], v[112:113], v[152:153]
	v_pk_fma_f32 v[152:153], v[114:115], v[114:115], v[152:153]
	s_waitcnt vmcnt(32)
	v_pk_mul_f32 v[154:155], v[116:117], v[116:117]
	v_pk_fma_f32 v[154:155], v[118:119], v[118:119], v[154:155]
	v_pk_fma_f32 v[154:155], v[120:121], v[120:121], v[154:155]
	v_pk_fma_f32 v[154:155], v[122:123], v[122:123], v[154:155]
	v_pk_fma_f32 v[154:155], v[124:125], v[124:125], v[154:155]
	v_pk_fma_f32 v[154:155], v[126:127], v[126:127], v[154:155]
	v_pk_fma_f32 v[154:155], v[128:129], v[128:129], v[154:155]
	v_pk_fma_f32 v[154:155], v[130:131], v[130:131], v[154:155]
	v_add_f32_e32 v148, v148, v149
	v_add_f32_e32 v150, v150, v151
	v_add_f32_e32 v152, v152, v153
	v_add_f32_e32 v154, v154, v155
	s_nop 0
	v_add_f32_dpp v148, v148, v148 quad_perm:[1,0,3,2] row_mask:0xf bank_mask:0xf
	v_add_f32_dpp v150, v150, v150 quad_perm:[1,0,3,2] row_mask:0xf bank_mask:0xf
	v_add_f32_dpp v152, v152, v152 quad_perm:[1,0,3,2] row_mask:0xf bank_mask:0xf
	v_add_f32_dpp v154, v154, v154 quad_perm:[1,0,3,2] row_mask:0xf bank_mask:0xf
	s_nop 0
	v_add_f32_dpp v148, v148, v148 quad_perm:[2,3,0,1] row_mask:0xf bank_mask:0xf
	v_add_f32_dpp v150, v150, v150 quad_perm:[2,3,0,1] row_mask:0xf bank_mask:0xf
	v_add_f32_dpp v152, v152, v152 quad_perm:[2,3,0,1] row_mask:0xf bank_mask:0xf
	v_add_f32_dpp v154, v154, v154 quad_perm:[2,3,0,1] row_mask:0xf bank_mask:0xf
	s_nop 0
	v_add_f32_dpp v148, v148, v148 row_half_mirror row_mask:0xf bank_mask:0xf
	v_add_f32_dpp v150, v150, v150 row_half_mirror row_mask:0xf bank_mask:0xf
	v_add_f32_dpp v152, v152, v152 row_half_mirror row_mask:0xf bank_mask:0xf
	v_add_f32_dpp v154, v154, v154 row_half_mirror row_mask:0xf bank_mask:0xf
	s_nop 0
	v_add_f32_dpp v148, v148, v148 row_mirror row_mask:0xf bank_mask:0xf
	v_add_f32_dpp v150, v150, v150 row_mirror row_mask:0xf bank_mask:0xf
	v_add_f32_dpp v152, v152, v152 row_mirror row_mask:0xf bank_mask:0xf
	v_add_f32_dpp v154, v154, v154 row_mirror row_mask:0xf bank_mask:0xf
	s_nop 0
	v_add_f32_dpp v148, v148, v148 row_bcast:15 row_mask:0xa bank_mask:0xf
	v_add_f32_dpp v150, v150, v150 row_bcast:15 row_mask:0xa bank_mask:0xf
	v_add_f32_dpp v152, v152, v152 row_bcast:15 row_mask:0xa bank_mask:0xf
	v_add_f32_dpp v154, v154, v154 row_bcast:15 row_mask:0xa bank_mask:0xf
	s_nop 0
	v_add_f32_dpp v148, v148, v148 row_bcast:31 row_mask:0xc bank_mask:0xf
	v_add_f32_dpp v150, v150, v150 row_bcast:31 row_mask:0xc bank_mask:0xf
	v_add_f32_dpp v152, v152, v152 row_bcast:31 row_mask:0xc bank_mask:0xf
	v_add_f32_dpp v154, v154, v154 row_bcast:31 row_mask:0xc bank_mask:0xf
	s_nop 1
	v_readlane_b32 s0, v148, 63
	v_readlane_b32 s1, v150, 63
	v_readlane_b32 s2, v152, 63
	v_readlane_b32 s3, v154, 63
	s_nop 1
	v_mov_b32_e32 v156, s0
	v_mov_b32_e32 v158, s1
	v_mov_b32_e32 v160, s2
	v_mov_b32_e32 v162, s3
	v_fmamk_f32 v156, v156, 0x3a800000, v196
	v_fmamk_f32 v158, v158, 0x3a800000, v196
	v_fmamk_f32 v160, v160, 0x3a800000, v196
	v_fmamk_f32 v162, v162, 0x3a800000, v196
	v_rsq_f32_e32 v156, v156
	v_rsq_f32_e32 v158, v158
	v_rsq_f32_e32 v160, v160
	v_rsq_f32_e32 v162, v162
	s_nop 0
	v_pk_mul_f32 v[68:69], v[68:69], v[156:157] op_sel_hi:[1,0]
	v_pk_mul_f32 v[70:71], v[70:71], v[156:157] op_sel_hi:[1,0]
	v_pk_mul_f32 v[72:73], v[72:73], v[156:157] op_sel_hi:[1,0]
	v_pk_mul_f32 v[74:75], v[74:75], v[156:157] op_sel_hi:[1,0]
	v_pk_mul_f32 v[76:77], v[76:77], v[156:157] op_sel_hi:[1,0]
	v_pk_mul_f32 v[78:79], v[78:79], v[156:157] op_sel_hi:[1,0]
	v_pk_mul_f32 v[80:81], v[80:81], v[156:157] op_sel_hi:[1,0]
	v_pk_mul_f32 v[82:83], v[82:83], v[156:157] op_sel_hi:[1,0]
	v_pk_mul_f32 v[68:69], v[68:69], v[132:133]
	v_pk_mul_f32 v[70:71], v[70:71], v[134:135]
	v_pk_mul_f32 v[72:73], v[72:73], v[136:137]
	v_pk_mul_f32 v[74:75], v[74:75], v[138:139]
	v_pk_mul_f32 v[76:77], v[76:77], v[140:141]
	v_pk_mul_f32 v[78:79], v[78:79], v[142:143]
	v_pk_mul_f32 v[80:81], v[80:81], v[144:145]
	v_pk_mul_f32 v[82:83], v[82:83], v[146:147]
	v_cvt_pk_bf16_f32 v68, v68, v69
	v_cvt_pk_bf16_f32 v69, v70, v71
	v_cvt_pk_bf16_f32 v70, v72, v73
	v_cvt_pk_bf16_f32 v71, v74, v75
	v_cvt_pk_bf16_f32 v72, v76, v77
	v_cvt_pk_bf16_f32 v73, v78, v79
	v_cvt_pk_bf16_f32 v74, v80, v81
	v_cvt_pk_bf16_f32 v75, v82, v83
	s_add_u32 s24, s12, 0x1000000
	s_addc_u32 s25, s13, 0
	global_store_dwordx2 v165, v[68:69], s[24:25] offset:0
	global_store_dwordx2 v165, v[70:71], s[24:25] offset:512
	global_store_dwordx2 v165, v[72:73], s[24:25] offset:1024
	global_store_dwordx2 v165, v[74:75], s[24:25] offset:1536
	v_pk_mul_f32 v[84:85], v[84:85], v[158:159] op_sel_hi:[1,0]
	v_pk_mul_f32 v[86:87], v[86:87], v[158:159] op_sel_hi:[1,0]
	v_pk_mul_f32 v[88:89], v[88:89], v[158:159] op_sel_hi:[1,0]
	v_pk_mul_f32 v[90:91], v[90:91], v[158:159] op_sel_hi:[1,0]
	v_pk_mul_f32 v[92:93], v[92:93], v[158:159] op_sel_hi:[1,0]
	v_pk_mul_f32 v[94:95], v[94:95], v[158:159] op_sel_hi:[1,0]
	v_pk_mul_f32 v[96:97], v[96:97], v[158:159] op_sel_hi:[1,0]
	v_pk_mul_f32 v[98:99], v[98:99], v[158:159] op_sel_hi:[1,0]
	v_pk_mul_f32 v[84:85], v[84:85], v[132:133]
	v_pk_mul_f32 v[86:87], v[86:87], v[134:135]
	v_pk_mul_f32 v[88:89], v[88:89], v[136:137]
	v_pk_mul_f32 v[90:91], v[90:91], v[138:139]
	v_pk_mul_f32 v[92:93], v[92:93], v[140:141]
	v_pk_mul_f32 v[94:95], v[94:95], v[142:143]
	v_pk_mul_f32 v[96:97], v[96:97], v[144:145]
	v_pk_mul_f32 v[98:99], v[98:99], v[146:147]
	v_cvt_pk_bf16_f32 v84, v84, v85
	v_cvt_pk_bf16_f32 v85, v86, v87
	v_cvt_pk_bf16_f32 v86, v88, v89
	v_cvt_pk_bf16_f32 v87, v90, v91
	v_cvt_pk_bf16_f32 v88, v92, v93
	v_cvt_pk_bf16_f32 v89, v94, v95
	v_cvt_pk_bf16_f32 v90, v96, v97
	v_cvt_pk_bf16_f32 v91, v98, v99
	s_add_u32 s24, s12, 0x1400000
	s_addc_u32 s25, s13, 0
	global_store_dwordx2 v165, v[84:85], s[24:25] offset:0
	global_store_dwordx2 v165, v[86:87], s[24:25] offset:512
	global_store_dwordx2 v165, v[88:89], s[24:25] offset:1024
	global_store_dwordx2 v165, v[90:91], s[24:25] offset:1536
	v_pk_mul_f32 v[100:101], v[100:101], v[160:161] op_sel_hi:[1,0]
	v_pk_mul_f32 v[102:103], v[102:103], v[160:161] op_sel_hi:[1,0]
	v_pk_mul_f32 v[104:105], v[104:105], v[160:161] op_sel_hi:[1,0]
	v_pk_mul_f32 v[106:107], v[106:107], v[160:161] op_sel_hi:[1,0]
	v_pk_mul_f32 v[108:109], v[108:109], v[160:161] op_sel_hi:[1,0]
	v_pk_mul_f32 v[110:111], v[110:111], v[160:161] op_sel_hi:[1,0]
	v_pk_mul_f32 v[112:113], v[112:113], v[160:161] op_sel_hi:[1,0]
	v_pk_mul_f32 v[114:115], v[114:115], v[160:161] op_sel_hi:[1,0]
	v_pk_mul_f32 v[100:101], v[100:101], v[132:133]
	v_pk_mul_f32 v[102:103], v[102:103], v[134:135]
	v_pk_mul_f32 v[104:105], v[104:105], v[136:137]
	v_pk_mul_f32 v[106:107], v[106:107], v[138:139]
	v_pk_mul_f32 v[108:109], v[108:109], v[140:141]
	v_pk_mul_f32 v[110:111], v[110:111], v[142:143]
	v_pk_mul_f32 v[112:113], v[112:113], v[144:145]
	v_pk_mul_f32 v[114:115], v[114:115], v[146:147]
	v_cvt_pk_bf16_f32 v100, v100, v101
	v_cvt_pk_bf16_f32 v101, v102, v103
	v_cvt_pk_bf16_f32 v102, v104, v105
	v_cvt_pk_bf16_f32 v103, v106, v107
	v_cvt_pk_bf16_f32 v104, v108, v109
	v_cvt_pk_bf16_f32 v105, v110, v111
	v_cvt_pk_bf16_f32 v106, v112, v113
	v_cvt_pk_bf16_f32 v107, v114, v115
	s_add_u32 s24, s12, 0x1800000
	s_addc_u32 s25, s13, 0
	global_store_dwordx2 v165, v[100:101], s[24:25] offset:0
	global_store_dwordx2 v165, v[102:103], s[24:25] offset:512
	global_store_dwordx2 v165, v[104:105], s[24:25] offset:1024
	global_store_dwordx2 v165, v[106:107], s[24:25] offset:1536
	v_pk_mul_f32 v[116:117], v[116:117], v[162:163] op_sel_hi:[1,0]
	v_pk_mul_f32 v[118:119], v[118:119], v[162:163] op_sel_hi:[1,0]
	v_pk_mul_f32 v[120:121], v[120:121], v[162:163] op_sel_hi:[1,0]
	v_pk_mul_f32 v[122:123], v[122:123], v[162:163] op_sel_hi:[1,0]
	v_pk_mul_f32 v[124:125], v[124:125], v[162:163] op_sel_hi:[1,0]
	v_pk_mul_f32 v[126:127], v[126:127], v[162:163] op_sel_hi:[1,0]
	v_pk_mul_f32 v[128:129], v[128:129], v[162:163] op_sel_hi:[1,0]
	v_pk_mul_f32 v[130:131], v[130:131], v[162:163] op_sel_hi:[1,0]
	v_pk_mul_f32 v[116:117], v[116:117], v[132:133]
	v_pk_mul_f32 v[118:119], v[118:119], v[134:135]
	v_pk_mul_f32 v[120:121], v[120:121], v[136:137]
	v_pk_mul_f32 v[122:123], v[122:123], v[138:139]
	v_pk_mul_f32 v[124:125], v[124:125], v[140:141]
	v_pk_mul_f32 v[126:127], v[126:127], v[142:143]
	v_pk_mul_f32 v[128:129], v[128:129], v[144:145]
	v_pk_mul_f32 v[130:131], v[130:131], v[146:147]
	v_cvt_pk_bf16_f32 v116, v116, v117
	v_cvt_pk_bf16_f32 v117, v118, v119
	v_cvt_pk_bf16_f32 v118, v120, v121
	v_cvt_pk_bf16_f32 v119, v122, v123
	v_cvt_pk_bf16_f32 v120, v124, v125
	v_cvt_pk_bf16_f32 v121, v126, v127
	v_cvt_pk_bf16_f32 v122, v128, v129
	v_cvt_pk_bf16_f32 v123, v130, v131
	s_add_u32 s24, s12, 0x1c00000
	s_addc_u32 s25, s13, 0
	global_store_dwordx2 v165, v[116:117], s[24:25] offset:0
	global_store_dwordx2 v165, v[118:119], s[24:25] offset:512
	global_store_dwordx2 v165, v[120:121], s[24:25] offset:1024
	global_store_dwordx2 v165, v[122:123], s[24:25] offset:1536
	s_add_u32 s22, s10, 0x6000000
	s_addc_u32 s23, s11, 0
	global_load_dwordx4 v[68:71], v164, s[22:23] offset:0 nt
	global_load_dwordx4 v[72:75], v164, s[22:23] offset:1024 nt
	global_load_dwordx4 v[76:79], v164, s[22:23] offset:2048 nt
	global_load_dwordx4 v[80:83], v164, s[22:23] offset:3072 nt
	s_add_u32 s22, s10, 0x6800000
	s_addc_u32 s23, s11, 0
	global_load_dwordx4 v[84:87], v164, s[22:23] offset:0 nt
	global_load_dwordx4 v[88:91], v164, s[22:23] offset:1024 nt
	global_load_dwordx4 v[92:95], v164, s[22:23] offset:2048 nt
	global_load_dwordx4 v[96:99], v164, s[22:23] offset:3072 nt
	s_add_u32 s22, s10, 0x7000000
	s_addc_u32 s23, s11, 0
	global_load_dwordx4 v[100:103], v164, s[22:23] offset:0 nt
	global_load_dwordx4 v[104:107], v164, s[22:23] offset:1024 nt
	global_load_dwordx4 v[108:111], v164, s[22:23] offset:2048 nt
	global_load_dwordx4 v[112:115], v164, s[22:23] offset:3072 nt
	s_add_u32 s22, s10, 0x7800000
	s_addc_u32 s23, s11, 0
	global_load_dwordx4 v[116:119], v164, s[22:23] offset:0 nt
	global_load_dwordx4 v[120:123], v164, s[22:23] offset:1024 nt
	global_load_dwordx4 v[124:127], v164, s[22:23] offset:2048 nt
	global_load_dwordx4 v[128:131], v164, s[22:23] offset:3072 nt
	s_waitcnt vmcnt(44)
	v_pk_mul_f32 v[148:149], v[4:5], v[4:5]
	v_pk_fma_f32 v[148:149], v[6:7], v[6:7], v[148:149]
	v_pk_fma_f32 v[148:149], v[8:9], v[8:9], v[148:149]
	v_pk_fma_f32 v[148:149], v[10:11], v[10:11], v[148:149]
	v_pk_fma_f32 v[148:149], v[12:13], v[12:13], v[148:149]
	v_pk_fma_f32 v[148:149], v[14:15], v[14:15], v[148:149]
	v_pk_fma_f32 v[148:149], v[16:17], v[16:17], v[148:149]
	v_pk_fma_f32 v[148:149], v[18:19], v[18:19], v[148:149]
	s_waitcnt vmcnt(40)
	v_pk_mul_f32 v[150:151], v[20:21], v[20:21]
	v_pk_fma_f32 v[150:151], v[22:23], v[22:23], v[150:151]
	v_pk_fma_f32 v[150:151], v[24:25], v[24:25], v[150:151]
	v_pk_fma_f32 v[150:151], v[26:27], v[26:27], v[150:151]
	v_pk_fma_f32 v[150:151], v[28:29], v[28:29], v[150:151]
	v_pk_fma_f32 v[150:151], v[30:31], v[30:31], v[150:151]
	v_pk_fma_f32 v[150:151], v[32:33], v[32:33], v[150:151]
	v_pk_fma_f32 v[150:151], v[34:35], v[34:35], v[150:151]
	s_waitcnt vmcnt(36)
	v_pk_mul_f32 v[152:153], v[36:37], v[36:37]
	v_pk_fma_f32 v[152:153], v[38:39], v[38:39], v[152:153]
	v_pk_fma_f32 v[152:153], v[40:41], v[40:41], v[152:153]
	v_pk_fma_f32 v[152:153], v[42:43], v[42:43], v[152:153]
	v_pk_fma_f32 v[152:153], v[44:45], v[44:45], v[152:153]
	v_pk_fma_f32 v[152:153], v[46:47], v[46:47], v[152:153]
	v_pk_fma_f32 v[152:153], v[48:49], v[48:49], v[152:153]
	v_pk_fma_f32 v[152:153], v[50:51], v[50:51], v[152:153]
	s_waitcnt vmcnt(32)
	v_pk_mul_f32 v[154:155], v[52:53], v[52:53]
	v_pk_fma_f32 v[154:155], v[54:55], v[54:55], v[154:155]
	v_pk_fma_f32 v[154:155], v[56:57], v[56:57], v[154:155]
	v_pk_fma_f32 v[154:155], v[58:59], v[58:59], v[154:155]
	v_pk_fma_f32 v[154:155], v[60:61], v[60:61], v[154:155]
	v_pk_fma_f32 v[154:155], v[62:63], v[62:63], v[154:155]
	v_pk_fma_f32 v[154:155], v[64:65], v[64:65], v[154:155]
	v_pk_fma_f32 v[154:155], v[66:67], v[66:67], v[154:155]
	v_add_f32_e32 v148, v148, v149
	v_add_f32_e32 v150, v150, v151
	v_add_f32_e32 v152, v152, v153
	v_add_f32_e32 v154, v154, v155
	s_nop 0
	v_add_f32_dpp v148, v148, v148 quad_perm:[1,0,3,2] row_mask:0xf bank_mask:0xf
	v_add_f32_dpp v150, v150, v150 quad_perm:[1,0,3,2] row_mask:0xf bank_mask:0xf
	v_add_f32_dpp v152, v152, v152 quad_perm:[1,0,3,2] row_mask:0xf bank_mask:0xf
	v_add_f32_dpp v154, v154, v154 quad_perm:[1,0,3,2] row_mask:0xf bank_mask:0xf
	s_nop 0
	v_add_f32_dpp v148, v148, v148 quad_perm:[2,3,0,1] row_mask:0xf bank_mask:0xf
	v_add_f32_dpp v150, v150, v150 quad_perm:[2,3,0,1] row_mask:0xf bank_mask:0xf
	v_add_f32_dpp v152, v152, v152 quad_perm:[2,3,0,1] row_mask:0xf bank_mask:0xf
	v_add_f32_dpp v154, v154, v154 quad_perm:[2,3,0,1] row_mask:0xf bank_mask:0xf
	s_nop 0
	v_add_f32_dpp v148, v148, v148 row_half_mirror row_mask:0xf bank_mask:0xf
	v_add_f32_dpp v150, v150, v150 row_half_mirror row_mask:0xf bank_mask:0xf
	v_add_f32_dpp v152, v152, v152 row_half_mirror row_mask:0xf bank_mask:0xf
	v_add_f32_dpp v154, v154, v154 row_half_mirror row_mask:0xf bank_mask:0xf
	s_nop 0
	v_add_f32_dpp v148, v148, v148 row_mirror row_mask:0xf bank_mask:0xf
	v_add_f32_dpp v150, v150, v150 row_mirror row_mask:0xf bank_mask:0xf
	v_add_f32_dpp v152, v152, v152 row_mirror row_mask:0xf bank_mask:0xf
	v_add_f32_dpp v154, v154, v154 row_mirror row_mask:0xf bank_mask:0xf
	s_nop 0
	v_add_f32_dpp v148, v148, v148 row_bcast:15 row_mask:0xa bank_mask:0xf
	v_add_f32_dpp v150, v150, v150 row_bcast:15 row_mask:0xa bank_mask:0xf
	v_add_f32_dpp v152, v152, v152 row_bcast:15 row_mask:0xa bank_mask:0xf
	v_add_f32_dpp v154, v154, v154 row_bcast:15 row_mask:0xa bank_mask:0xf
	s_nop 0
	v_add_f32_dpp v148, v148, v148 row_bcast:31 row_mask:0xc bank_mask:0xf
	v_add_f32_dpp v150, v150, v150 row_bcast:31 row_mask:0xc bank_mask:0xf
	v_add_f32_dpp v152, v152, v152 row_bcast:31 row_mask:0xc bank_mask:0xf
	v_add_f32_dpp v154, v154, v154 row_bcast:31 row_mask:0xc bank_mask:0xf
	s_nop 1
	v_readlane_b32 s0, v148, 63
	v_readlane_b32 s1, v150, 63
	v_readlane_b32 s2, v152, 63
	v_readlane_b32 s3, v154, 63
	s_nop 1
	v_mov_b32_e32 v156, s0
	v_mov_b32_e32 v158, s1
	v_mov_b32_e32 v160, s2
	v_mov_b32_e32 v162, s3
	v_fmamk_f32 v156, v156, 0x3a800000, v196
	v_fmamk_f32 v158, v158, 0x3a800000, v196
	v_fmamk_f32 v160, v160, 0x3a800000, v196
	v_fmamk_f32 v162, v162, 0x3a800000, v196
	v_rsq_f32_e32 v156, v156
	v_rsq_f32_e32 v158, v158
	v_rsq_f32_e32 v160, v160
	v_rsq_f32_e32 v162, v162
	s_nop 0
	v_pk_mul_f32 v[4:5], v[4:5], v[156:157] op_sel_hi:[1,0]
	v_pk_mul_f32 v[6:7], v[6:7], v[156:157] op_sel_hi:[1,0]
	v_pk_mul_f32 v[8:9], v[8:9], v[156:157] op_sel_hi:[1,0]
	v_pk_mul_f32 v[10:11], v[10:11], v[156:157] op_sel_hi:[1,0]
	v_pk_mul_f32 v[12:13], v[12:13], v[156:157] op_sel_hi:[1,0]
	v_pk_mul_f32 v[14:15], v[14:15], v[156:157] op_sel_hi:[1,0]
	v_pk_mul_f32 v[16:17], v[16:17], v[156:157] op_sel_hi:[1,0]
	v_pk_mul_f32 v[18:19], v[18:19], v[156:157] op_sel_hi:[1,0]
	v_pk_mul_f32 v[4:5], v[4:5], v[132:133]
	v_pk_mul_f32 v[6:7], v[6:7], v[134:135]
	v_pk_mul_f32 v[8:9], v[8:9], v[136:137]
	v_pk_mul_f32 v[10:11], v[10:11], v[138:139]
	v_pk_mul_f32 v[12:13], v[12:13], v[140:141]
	v_pk_mul_f32 v[14:15], v[14:15], v[142:143]
	v_pk_mul_f32 v[16:17], v[16:17], v[144:145]
	v_pk_mul_f32 v[18:19], v[18:19], v[146:147]
	v_cvt_pk_bf16_f32 v4, v4, v5
	v_cvt_pk_bf16_f32 v5, v6, v7
	v_cvt_pk_bf16_f32 v6, v8, v9
	v_cvt_pk_bf16_f32 v7, v10, v11
	v_cvt_pk_bf16_f32 v8, v12, v13
	v_cvt_pk_bf16_f32 v9, v14, v15
	v_cvt_pk_bf16_f32 v10, v16, v17
	v_cvt_pk_bf16_f32 v11, v18, v19
	s_add_u32 s24, s12, 0x2000000
	s_addc_u32 s25, s13, 0
	global_store_dwordx2 v165, v[4:5], s[24:25] offset:0
	global_store_dwordx2 v165, v[6:7], s[24:25] offset:512
	global_store_dwordx2 v165, v[8:9], s[24:25] offset:1024
	global_store_dwordx2 v165, v[10:11], s[24:25] offset:1536
	v_pk_mul_f32 v[20:21], v[20:21], v[158:159] op_sel_hi:[1,0]
	v_pk_mul_f32 v[22:23], v[22:23], v[158:159] op_sel_hi:[1,0]
	v_pk_mul_f32 v[24:25], v[24:25], v[158:159] op_sel_hi:[1,0]
	v_pk_mul_f32 v[26:27], v[26:27], v[158:159] op_sel_hi:[1,0]
	v_pk_mul_f32 v[28:29], v[28:29], v[158:159] op_sel_hi:[1,0]
	v_pk_mul_f32 v[30:31], v[30:31], v[158:159] op_sel_hi:[1,0]
	v_pk_mul_f32 v[32:33], v[32:33], v[158:159] op_sel_hi:[1,0]
	v_pk_mul_f32 v[34:35], v[34:35], v[158:159] op_sel_hi:[1,0]
	v_pk_mul_f32 v[20:21], v[20:21], v[132:133]
	v_pk_mul_f32 v[22:23], v[22:23], v[134:135]
	v_pk_mul_f32 v[24:25], v[24:25], v[136:137]
	v_pk_mul_f32 v[26:27], v[26:27], v[138:139]
	v_pk_mul_f32 v[28:29], v[28:29], v[140:141]
	v_pk_mul_f32 v[30:31], v[30:31], v[142:143]
	v_pk_mul_f32 v[32:33], v[32:33], v[144:145]
	v_pk_mul_f32 v[34:35], v[34:35], v[146:147]
	v_cvt_pk_bf16_f32 v20, v20, v21
	v_cvt_pk_bf16_f32 v21, v22, v23
	v_cvt_pk_bf16_f32 v22, v24, v25
	v_cvt_pk_bf16_f32 v23, v26, v27
	v_cvt_pk_bf16_f32 v24, v28, v29
	v_cvt_pk_bf16_f32 v25, v30, v31
	v_cvt_pk_bf16_f32 v26, v32, v33
	v_cvt_pk_bf16_f32 v27, v34, v35
	s_add_u32 s24, s12, 0x2400000
	s_addc_u32 s25, s13, 0
	global_store_dwordx2 v165, v[20:21], s[24:25] offset:0
	global_store_dwordx2 v165, v[22:23], s[24:25] offset:512
	global_store_dwordx2 v165, v[24:25], s[24:25] offset:1024
	global_store_dwordx2 v165, v[26:27], s[24:25] offset:1536
	v_pk_mul_f32 v[36:37], v[36:37], v[160:161] op_sel_hi:[1,0]
	v_pk_mul_f32 v[38:39], v[38:39], v[160:161] op_sel_hi:[1,0]
	v_pk_mul_f32 v[40:41], v[40:41], v[160:161] op_sel_hi:[1,0]
	v_pk_mul_f32 v[42:43], v[42:43], v[160:161] op_sel_hi:[1,0]
	v_pk_mul_f32 v[44:45], v[44:45], v[160:161] op_sel_hi:[1,0]
	v_pk_mul_f32 v[46:47], v[46:47], v[160:161] op_sel_hi:[1,0]
	v_pk_mul_f32 v[48:49], v[48:49], v[160:161] op_sel_hi:[1,0]
	v_pk_mul_f32 v[50:51], v[50:51], v[160:161] op_sel_hi:[1,0]
	v_pk_mul_f32 v[36:37], v[36:37], v[132:133]
	v_pk_mul_f32 v[38:39], v[38:39], v[134:135]
	v_pk_mul_f32 v[40:41], v[40:41], v[136:137]
	v_pk_mul_f32 v[42:43], v[42:43], v[138:139]
	v_pk_mul_f32 v[44:45], v[44:45], v[140:141]
	v_pk_mul_f32 v[46:47], v[46:47], v[142:143]
	v_pk_mul_f32 v[48:49], v[48:49], v[144:145]
	v_pk_mul_f32 v[50:51], v[50:51], v[146:147]
	v_cvt_pk_bf16_f32 v36, v36, v37
	v_cvt_pk_bf16_f32 v37, v38, v39
	v_cvt_pk_bf16_f32 v38, v40, v41
	v_cvt_pk_bf16_f32 v39, v42, v43
	v_cvt_pk_bf16_f32 v40, v44, v45
	v_cvt_pk_bf16_f32 v41, v46, v47
	v_cvt_pk_bf16_f32 v42, v48, v49
	v_cvt_pk_bf16_f32 v43, v50, v51
	s_add_u32 s24, s12, 0x2800000
	s_addc_u32 s25, s13, 0
	global_store_dwordx2 v165, v[36:37], s[24:25] offset:0
	global_store_dwordx2 v165, v[38:39], s[24:25] offset:512
	global_store_dwordx2 v165, v[40:41], s[24:25] offset:1024
	global_store_dwordx2 v165, v[42:43], s[24:25] offset:1536
	v_pk_mul_f32 v[52:53], v[52:53], v[162:163] op_sel_hi:[1,0]
	v_pk_mul_f32 v[54:55], v[54:55], v[162:163] op_sel_hi:[1,0]
	v_pk_mul_f32 v[56:57], v[56:57], v[162:163] op_sel_hi:[1,0]
	v_pk_mul_f32 v[58:59], v[58:59], v[162:163] op_sel_hi:[1,0]
	v_pk_mul_f32 v[60:61], v[60:61], v[162:163] op_sel_hi:[1,0]
	v_pk_mul_f32 v[62:63], v[62:63], v[162:163] op_sel_hi:[1,0]
	v_pk_mul_f32 v[64:65], v[64:65], v[162:163] op_sel_hi:[1,0]
	v_pk_mul_f32 v[66:67], v[66:67], v[162:163] op_sel_hi:[1,0]
	v_pk_mul_f32 v[52:53], v[52:53], v[132:133]
	v_pk_mul_f32 v[54:55], v[54:55], v[134:135]
	v_pk_mul_f32 v[56:57], v[56:57], v[136:137]
	v_pk_mul_f32 v[58:59], v[58:59], v[138:139]
	v_pk_mul_f32 v[60:61], v[60:61], v[140:141]
	v_pk_mul_f32 v[62:63], v[62:63], v[142:143]
	v_pk_mul_f32 v[64:65], v[64:65], v[144:145]
	v_pk_mul_f32 v[66:67], v[66:67], v[146:147]
	v_cvt_pk_bf16_f32 v52, v52, v53
	v_cvt_pk_bf16_f32 v53, v54, v55
	v_cvt_pk_bf16_f32 v54, v56, v57
	v_cvt_pk_bf16_f32 v55, v58, v59
	v_cvt_pk_bf16_f32 v56, v60, v61
	v_cvt_pk_bf16_f32 v57, v62, v63
	v_cvt_pk_bf16_f32 v58, v64, v65
	v_cvt_pk_bf16_f32 v59, v66, v67
	s_add_u32 s24, s12, 0x2c00000
	s_addc_u32 s25, s13, 0
	global_store_dwordx2 v165, v[52:53], s[24:25] offset:0
	global_store_dwordx2 v165, v[54:55], s[24:25] offset:512
	global_store_dwordx2 v165, v[56:57], s[24:25] offset:1024
	global_store_dwordx2 v165, v[58:59], s[24:25] offset:1536
	s_waitcnt vmcnt(28)
	v_pk_mul_f32 v[148:149], v[68:69], v[68:69]
	v_pk_fma_f32 v[148:149], v[70:71], v[70:71], v[148:149]
	v_pk_fma_f32 v[148:149], v[72:73], v[72:73], v[148:149]
	v_pk_fma_f32 v[148:149], v[74:75], v[74:75], v[148:149]
	v_pk_fma_f32 v[148:149], v[76:77], v[76:77], v[148:149]
	v_pk_fma_f32 v[148:149], v[78:79], v[78:79], v[148:149]
	v_pk_fma_f32 v[148:149], v[80:81], v[80:81], v[148:149]
	v_pk_fma_f32 v[148:149], v[82:83], v[82:83], v[148:149]
	s_waitcnt vmcnt(24)
	v_pk_mul_f32 v[150:151], v[84:85], v[84:85]
	v_pk_fma_f32 v[150:151], v[86:87], v[86:87], v[150:151]
	v_pk_fma_f32 v[150:151], v[88:89], v[88:89], v[150:151]
	v_pk_fma_f32 v[150:151], v[90:91], v[90:91], v[150:151]
	v_pk_fma_f32 v[150:151], v[92:93], v[92:93], v[150:151]
	v_pk_fma_f32 v[150:151], v[94:95], v[94:95], v[150:151]
	v_pk_fma_f32 v[150:151], v[96:97], v[96:97], v[150:151]
	v_pk_fma_f32 v[150:151], v[98:99], v[98:99], v[150:151]
	s_waitcnt vmcnt(20)
	v_pk_mul_f32 v[152:153], v[100:101], v[100:101]
	v_pk_fma_f32 v[152:153], v[102:103], v[102:103], v[152:153]
	v_pk_fma_f32 v[152:153], v[104:105], v[104:105], v[152:153]
	v_pk_fma_f32 v[152:153], v[106:107], v[106:107], v[152:153]
	v_pk_fma_f32 v[152:153], v[108:109], v[108:109], v[152:153]
	v_pk_fma_f32 v[152:153], v[110:111], v[110:111], v[152:153]
	v_pk_fma_f32 v[152:153], v[112:113], v[112:113], v[152:153]
	v_pk_fma_f32 v[152:153], v[114:115], v[114:115], v[152:153]
	s_waitcnt vmcnt(16)
	v_pk_mul_f32 v[154:155], v[116:117], v[116:117]
	v_pk_fma_f32 v[154:155], v[118:119], v[118:119], v[154:155]
	v_pk_fma_f32 v[154:155], v[120:121], v[120:121], v[154:155]
	v_pk_fma_f32 v[154:155], v[122:123], v[122:123], v[154:155]
	v_pk_fma_f32 v[154:155], v[124:125], v[124:125], v[154:155]
	v_pk_fma_f32 v[154:155], v[126:127], v[126:127], v[154:155]
	v_pk_fma_f32 v[154:155], v[128:129], v[128:129], v[154:155]
	v_pk_fma_f32 v[154:155], v[130:131], v[130:131], v[154:155]
	v_add_f32_e32 v148, v148, v149
	v_add_f32_e32 v150, v150, v151
	v_add_f32_e32 v152, v152, v153
	v_add_f32_e32 v154, v154, v155
	s_nop 0
	v_add_f32_dpp v148, v148, v148 quad_perm:[1,0,3,2] row_mask:0xf bank_mask:0xf
	v_add_f32_dpp v150, v150, v150 quad_perm:[1,0,3,2] row_mask:0xf bank_mask:0xf
	v_add_f32_dpp v152, v152, v152 quad_perm:[1,0,3,2] row_mask:0xf bank_mask:0xf
	v_add_f32_dpp v154, v154, v154 quad_perm:[1,0,3,2] row_mask:0xf bank_mask:0xf
	s_nop 0
	v_add_f32_dpp v148, v148, v148 quad_perm:[2,3,0,1] row_mask:0xf bank_mask:0xf
	v_add_f32_dpp v150, v150, v150 quad_perm:[2,3,0,1] row_mask:0xf bank_mask:0xf
	v_add_f32_dpp v152, v152, v152 quad_perm:[2,3,0,1] row_mask:0xf bank_mask:0xf
	v_add_f32_dpp v154, v154, v154 quad_perm:[2,3,0,1] row_mask:0xf bank_mask:0xf
	s_nop 0
	v_add_f32_dpp v148, v148, v148 row_half_mirror row_mask:0xf bank_mask:0xf
	v_add_f32_dpp v150, v150, v150 row_half_mirror row_mask:0xf bank_mask:0xf
	v_add_f32_dpp v152, v152, v152 row_half_mirror row_mask:0xf bank_mask:0xf
	v_add_f32_dpp v154, v154, v154 row_half_mirror row_mask:0xf bank_mask:0xf
	s_nop 0
	v_add_f32_dpp v148, v148, v148 row_mirror row_mask:0xf bank_mask:0xf
	v_add_f32_dpp v150, v150, v150 row_mirror row_mask:0xf bank_mask:0xf
	v_add_f32_dpp v152, v152, v152 row_mirror row_mask:0xf bank_mask:0xf
	v_add_f32_dpp v154, v154, v154 row_mirror row_mask:0xf bank_mask:0xf
	s_nop 0
	v_add_f32_dpp v148, v148, v148 row_bcast:15 row_mask:0xa bank_mask:0xf
	v_add_f32_dpp v150, v150, v150 row_bcast:15 row_mask:0xa bank_mask:0xf
	v_add_f32_dpp v152, v152, v152 row_bcast:15 row_mask:0xa bank_mask:0xf
	v_add_f32_dpp v154, v154, v154 row_bcast:15 row_mask:0xa bank_mask:0xf
	s_nop 0
	v_add_f32_dpp v148, v148, v148 row_bcast:31 row_mask:0xc bank_mask:0xf
	v_add_f32_dpp v150, v150, v150 row_bcast:31 row_mask:0xc bank_mask:0xf
	v_add_f32_dpp v152, v152, v152 row_bcast:31 row_mask:0xc bank_mask:0xf
	v_add_f32_dpp v154, v154, v154 row_bcast:31 row_mask:0xc bank_mask:0xf
	s_nop 1
	v_readlane_b32 s0, v148, 63
	v_readlane_b32 s1, v150, 63
	v_readlane_b32 s2, v152, 63
	v_readlane_b32 s3, v154, 63
	s_nop 1
	v_mov_b32_e32 v156, s0
	v_mov_b32_e32 v158, s1
	v_mov_b32_e32 v160, s2
	v_mov_b32_e32 v162, s3
	v_fmamk_f32 v156, v156, 0x3a800000, v196
	v_fmamk_f32 v158, v158, 0x3a800000, v196
	v_fmamk_f32 v160, v160, 0x3a800000, v196
	v_fmamk_f32 v162, v162, 0x3a800000, v196
	v_rsq_f32_e32 v156, v156
	v_rsq_f32_e32 v158, v158
	v_rsq_f32_e32 v160, v160
	v_rsq_f32_e32 v162, v162
	s_nop 0
	v_pk_mul_f32 v[68:69], v[68:69], v[156:157] op_sel_hi:[1,0]
	v_pk_mul_f32 v[70:71], v[70:71], v[156:157] op_sel_hi:[1,0]
	v_pk_mul_f32 v[72:73], v[72:73], v[156:157] op_sel_hi:[1,0]
	v_pk_mul_f32 v[74:75], v[74:75], v[156:157] op_sel_hi:[1,0]
	v_pk_mul_f32 v[76:77], v[76:77], v[156:157] op_sel_hi:[1,0]
	v_pk_mul_f32 v[78:79], v[78:79], v[156:157] op_sel_hi:[1,0]
	v_pk_mul_f32 v[80:81], v[80:81], v[156:157] op_sel_hi:[1,0]
	v_pk_mul_f32 v[82:83], v[82:83], v[156:157] op_sel_hi:[1,0]
	v_pk_mul_f32 v[68:69], v[68:69], v[132:133]
	v_pk_mul_f32 v[70:71], v[70:71], v[134:135]
	v_pk_mul_f32 v[72:73], v[72:73], v[136:137]
	v_pk_mul_f32 v[74:75], v[74:75], v[138:139]
	v_pk_mul_f32 v[76:77], v[76:77], v[140:141]
	v_pk_mul_f32 v[78:79], v[78:79], v[142:143]
	v_pk_mul_f32 v[80:81], v[80:81], v[144:145]
	v_pk_mul_f32 v[82:83], v[82:83], v[146:147]
	v_cvt_pk_bf16_f32 v68, v68, v69
	v_cvt_pk_bf16_f32 v69, v70, v71
	v_cvt_pk_bf16_f32 v70, v72, v73
	v_cvt_pk_bf16_f32 v71, v74, v75
	v_cvt_pk_bf16_f32 v72, v76, v77
	v_cvt_pk_bf16_f32 v73, v78, v79
	v_cvt_pk_bf16_f32 v74, v80, v81
	v_cvt_pk_bf16_f32 v75, v82, v83
	s_add_u32 s24, s12, 0x3000000
	s_addc_u32 s25, s13, 0
	global_store_dwordx2 v165, v[68:69], s[24:25] offset:0
	global_store_dwordx2 v165, v[70:71], s[24:25] offset:512
	global_store_dwordx2 v165, v[72:73], s[24:25] offset:1024
	global_store_dwordx2 v165, v[74:75], s[24:25] offset:1536
	v_pk_mul_f32 v[84:85], v[84:85], v[158:159] op_sel_hi:[1,0]
	v_pk_mul_f32 v[86:87], v[86:87], v[158:159] op_sel_hi:[1,0]
	v_pk_mul_f32 v[88:89], v[88:89], v[158:159] op_sel_hi:[1,0]
	v_pk_mul_f32 v[90:91], v[90:91], v[158:159] op_sel_hi:[1,0]
	v_pk_mul_f32 v[92:93], v[92:93], v[158:159] op_sel_hi:[1,0]
	v_pk_mul_f32 v[94:95], v[94:95], v[158:159] op_sel_hi:[1,0]
	v_pk_mul_f32 v[96:97], v[96:97], v[158:159] op_sel_hi:[1,0]
	v_pk_mul_f32 v[98:99], v[98:99], v[158:159] op_sel_hi:[1,0]
	v_pk_mul_f32 v[84:85], v[84:85], v[132:133]
	v_pk_mul_f32 v[86:87], v[86:87], v[134:135]
	v_pk_mul_f32 v[88:89], v[88:89], v[136:137]
	v_pk_mul_f32 v[90:91], v[90:91], v[138:139]
	v_pk_mul_f32 v[92:93], v[92:93], v[140:141]
	v_pk_mul_f32 v[94:95], v[94:95], v[142:143]
	v_pk_mul_f32 v[96:97], v[96:97], v[144:145]
	v_pk_mul_f32 v[98:99], v[98:99], v[146:147]
	v_cvt_pk_bf16_f32 v84, v84, v85
	v_cvt_pk_bf16_f32 v85, v86, v87
	v_cvt_pk_bf16_f32 v86, v88, v89
	v_cvt_pk_bf16_f32 v87, v90, v91
	v_cvt_pk_bf16_f32 v88, v92, v93
	v_cvt_pk_bf16_f32 v89, v94, v95
	v_cvt_pk_bf16_f32 v90, v96, v97
	v_cvt_pk_bf16_f32 v91, v98, v99
	s_add_u32 s24, s12, 0x3400000
	s_addc_u32 s25, s13, 0
	global_store_dwordx2 v165, v[84:85], s[24:25] offset:0
	global_store_dwordx2 v165, v[86:87], s[24:25] offset:512
	global_store_dwordx2 v165, v[88:89], s[24:25] offset:1024
	global_store_dwordx2 v165, v[90:91], s[24:25] offset:1536
	v_pk_mul_f32 v[100:101], v[100:101], v[160:161] op_sel_hi:[1,0]
	v_pk_mul_f32 v[102:103], v[102:103], v[160:161] op_sel_hi:[1,0]
	v_pk_mul_f32 v[104:105], v[104:105], v[160:161] op_sel_hi:[1,0]
	v_pk_mul_f32 v[106:107], v[106:107], v[160:161] op_sel_hi:[1,0]
	v_pk_mul_f32 v[108:109], v[108:109], v[160:161] op_sel_hi:[1,0]
	v_pk_mul_f32 v[110:111], v[110:111], v[160:161] op_sel_hi:[1,0]
	v_pk_mul_f32 v[112:113], v[112:113], v[160:161] op_sel_hi:[1,0]
	v_pk_mul_f32 v[114:115], v[114:115], v[160:161] op_sel_hi:[1,0]
	v_pk_mul_f32 v[100:101], v[100:101], v[132:133]
	v_pk_mul_f32 v[102:103], v[102:103], v[134:135]
	v_pk_mul_f32 v[104:105], v[104:105], v[136:137]
	v_pk_mul_f32 v[106:107], v[106:107], v[138:139]
	v_pk_mul_f32 v[108:109], v[108:109], v[140:141]
	v_pk_mul_f32 v[110:111], v[110:111], v[142:143]
	v_pk_mul_f32 v[112:113], v[112:113], v[144:145]
	v_pk_mul_f32 v[114:115], v[114:115], v[146:147]
	v_cvt_pk_bf16_f32 v100, v100, v101
	v_cvt_pk_bf16_f32 v101, v102, v103
	v_cvt_pk_bf16_f32 v102, v104, v105
	v_cvt_pk_bf16_f32 v103, v106, v107
	v_cvt_pk_bf16_f32 v104, v108, v109
	v_cvt_pk_bf16_f32 v105, v110, v111
	v_cvt_pk_bf16_f32 v106, v112, v113
	v_cvt_pk_bf16_f32 v107, v114, v115
	s_add_u32 s24, s12, 0x3800000
	s_addc_u32 s25, s13, 0
	global_store_dwordx2 v165, v[100:101], s[24:25] offset:0
	global_store_dwordx2 v165, v[102:103], s[24:25] offset:512
	global_store_dwordx2 v165, v[104:105], s[24:25] offset:1024
	global_store_dwordx2 v165, v[106:107], s[24:25] offset:1536
	v_pk_mul_f32 v[116:117], v[116:117], v[162:163] op_sel_hi:[1,0]
	v_pk_mul_f32 v[118:119], v[118:119], v[162:163] op_sel_hi:[1,0]
	v_pk_mul_f32 v[120:121], v[120:121], v[162:163] op_sel_hi:[1,0]
	v_pk_mul_f32 v[122:123], v[122:123], v[162:163] op_sel_hi:[1,0]
	v_pk_mul_f32 v[124:125], v[124:125], v[162:163] op_sel_hi:[1,0]
	v_pk_mul_f32 v[126:127], v[126:127], v[162:163] op_sel_hi:[1,0]
	v_pk_mul_f32 v[128:129], v[128:129], v[162:163] op_sel_hi:[1,0]
	v_pk_mul_f32 v[130:131], v[130:131], v[162:163] op_sel_hi:[1,0]
	v_pk_mul_f32 v[116:117], v[116:117], v[132:133]
	v_pk_mul_f32 v[118:119], v[118:119], v[134:135]
	v_pk_mul_f32 v[120:121], v[120:121], v[136:137]
	v_pk_mul_f32 v[122:123], v[122:123], v[138:139]
	v_pk_mul_f32 v[124:125], v[124:125], v[140:141]
	v_pk_mul_f32 v[126:127], v[126:127], v[142:143]
	v_pk_mul_f32 v[128:129], v[128:129], v[144:145]
	v_pk_mul_f32 v[130:131], v[130:131], v[146:147]
	v_cvt_pk_bf16_f32 v116, v116, v117
	v_cvt_pk_bf16_f32 v117, v118, v119
	v_cvt_pk_bf16_f32 v118, v120, v121
	v_cvt_pk_bf16_f32 v119, v122, v123
	v_cvt_pk_bf16_f32 v120, v124, v125
	v_cvt_pk_bf16_f32 v121, v126, v127
	v_cvt_pk_bf16_f32 v122, v128, v129
	v_cvt_pk_bf16_f32 v123, v130, v131
	s_add_u32 s24, s12, 0x3c00000
	s_addc_u32 s25, s13, 0
	global_store_dwordx2 v165, v[116:117], s[24:25] offset:0
	global_store_dwordx2 v165, v[118:119], s[24:25] offset:512
	global_store_dwordx2 v165, v[120:121], s[24:25] offset:1024
	global_store_dwordx2 v165, v[122:123], s[24:25] offset:1536
	s_cmpk_ge_u32 s20, 0x100
	s_cbranch_scc1 .Lrow0_done
	s_lshl_b32 s0, s20, 11
	s_add_u32 s14, s92, 0x3c00000
	s_addc_u32 s15, s93, 0
	s_add_u32 s14, s14, s0
	s_addc_u32 s15, s15, 0
	s_cmpk_ge_u32 s20, 16
	s_cbranch_scc1 .Lrow0_zero
	s_lshl_b32 s0, s20, 12
	s_add_u32 s22, s6, s0
	s_addc_u32 s23, s7, 0
	global_load_dwordx4 v[4:7], v164, s[22:23] offset:0
	global_load_dwordx4 v[8:11], v164, s[22:23] offset:1024
	global_load_dwordx4 v[12:15], v164, s[22:23] offset:2048
	global_load_dwordx4 v[16:19], v164, s[22:23] offset:3072
	s_waitcnt vmcnt(0)
	v_pk_mul_f32 v[148:149], v[4:5], v[4:5]
	v_pk_fma_f32 v[148:149], v[6:7], v[6:7], v[148:149]
	v_pk_fma_f32 v[148:149], v[8:9], v[8:9], v[148:149]
	v_pk_fma_f32 v[148:149], v[10:11], v[10:11], v[148:149]
	v_pk_fma_f32 v[148:149], v[12:13], v[12:13], v[148:149]
	v_pk_fma_f32 v[148:149], v[14:15], v[14:15], v[148:149]
	v_pk_fma_f32 v[148:149], v[16:17], v[16:17], v[148:149]
	v_pk_fma_f32 v[148:149], v[18:19], v[18:19], v[148:149]
	v_add_f32_e32 v148, v148, v149
	s_nop 1
	v_add_f32_dpp v148, v148, v148 quad_perm:[1,0,3,2] row_mask:0xf bank_mask:0xf
	s_nop 1
	v_add_f32_dpp v148, v148, v148 quad_perm:[2,3,0,1] row_mask:0xf bank_mask:0xf
	s_nop 1
	v_add_f32_dpp v148, v148, v148 row_half_mirror row_mask:0xf bank_mask:0xf
	s_nop 1
	v_add_f32_dpp v148, v148, v148 row_mirror row_mask:0xf bank_mask:0xf
	s_nop 1
	v_add_f32_dpp v148, v148, v148 row_bcast:15 row_mask:0xa bank_mask:0xf
	s_nop 1
	v_add_f32_dpp v148, v148, v148 row_bcast:31 row_mask:0xc bank_mask:0xf
	s_nop 1
	v_readlane_b32 s0, v148, 63
	s_nop 1
	v_mov_b32_e32 v156, s0
	v_fmamk_f32 v156, v156, 0x3a800000, v196
	v_rsq_f32_e32 v156, v156
	s_nop 0
	v_pk_mul_f32 v[4:5], v[4:5], v[156:157] op_sel_hi:[1,0]
	v_pk_mul_f32 v[6:7], v[6:7], v[156:157] op_sel_hi:[1,0]
	v_pk_mul_f32 v[8:9], v[8:9], v[156:157] op_sel_hi:[1,0]
	v_pk_mul_f32 v[10:11], v[10:11], v[156:157] op_sel_hi:[1,0]
	v_pk_mul_f32 v[12:13], v[12:13], v[156:157] op_sel_hi:[1,0]
	v_pk_mul_f32 v[14:15], v[14:15], v[156:157] op_sel_hi:[1,0]
	v_pk_mul_f32 v[16:17], v[16:17], v[156:157] op_sel_hi:[1,0]
	v_pk_mul_f32 v[18:19], v[18:19], v[156:157] op_sel_hi:[1,0]
	v_pk_mul_f32 v[4:5], v[4:5], v[132:133]
	v_pk_mul_f32 v[6:7], v[6:7], v[134:135]
	v_pk_mul_f32 v[8:9], v[8:9], v[136:137]
	v_pk_mul_f32 v[10:11], v[10:11], v[138:139]
	v_pk_mul_f32 v[12:13], v[12:13], v[140:141]
	v_pk_mul_f32 v[14:15], v[14:15], v[142:143]
	v_pk_mul_f32 v[16:17], v[16:17], v[144:145]
	v_pk_mul_f32 v[18:19], v[18:19], v[146:147]
	v_cvt_pk_bf16_f32 v4, v4, v5
	v_cvt_pk_bf16_f32 v5, v6, v7
	v_cvt_pk_bf16_f32 v6, v8, v9
	v_cvt_pk_bf16_f32 v7, v10, v11
	v_cvt_pk_bf16_f32 v8, v12, v13
	v_cvt_pk_bf16_f32 v9, v14, v15
	v_cvt_pk_bf16_f32 v10, v16, v17
	v_cvt_pk_bf16_f32 v11, v18, v19
	s_mov_b64 s[24:25], s[14:15]
	global_store_dwordx2 v165, v[4:5], s[24:25] offset:0
	global_store_dwordx2 v165, v[6:7], s[24:25] offset:512
	global_store_dwordx2 v165, v[8:9], s[24:25] offset:1024
	global_store_dwordx2 v165, v[10:11], s[24:25] offset:1536
	s_branch .Lrow0_done

.Lrow0_done:
	s_cmp_lg_u32 s99, 1
	s_cbranch_scc1 .Lp0_end
	s_mov_b32 s99, 2
	s_branch .Lp0_tr
